# grid barrier acquire, sound form: non-leader workgroups issue their agent-scope buffer_inv sc1 BEFORE the spin (their CU is idle, 1 WG/CU, so the L1 stays empty), XCD leader waits for its invalidate b
# baseline (speedup 1.0000x reference)
.LBB0_29:
	s_or_b64 exec, exec, s[14:15]
	v_cvt_f32_u32_e32 v5, v3
	s_waitcnt vmcnt(0)
	v_readfirstlane_b32 s11, v4
	v_sub_u32_e32 v4, 0, v3
	v_rcp_iflag_f32_e32 v5, v5
	v_add_u32_e32 v6, s11, v2
	v_mul_f32_e32 v5, 0x4f7ffffe, v5
	v_cvt_u32_f32_e32 v5, v5
	v_mul_lo_u32 v2, v4, v5
	v_mul_hi_u32 v2, v5, v2
	v_add_u32_e32 v2, v5, v2
	v_mul_hi_u32 v2, v6, v2
	v_mul_lo_u32 v4, v2, v3
	v_sub_u32_e32 v4, v6, v4
	v_add_u32_e32 v5, 1, v2
	v_cmp_ge_u32_e32 vcc, v4, v3
	s_nop 1
	v_cndmask_b32_e32 v2, v2, v5, vcc
	v_sub_u32_e32 v5, v4, v3
	v_cndmask_b32_e32 v4, v4, v5, vcc
	v_add_u32_e32 v5, 1, v2
	v_cmp_ge_u32_e32 vcc, v4, v3
	v_add_u32_e32 v4, 1, v6
	s_nop 0
	v_cndmask_b32_e32 v2, v2, v5, vcc
	v_mul_lo_u32 v5, v3, v2
	v_add_u32_e32 v3, v5, v3
	v_cmp_ne_u32_e32 vcc, v4, v3
	s_and_saveexec_b64 s[12:13], vcc
	s_xor_b64 s[12:13], exec, s[12:13]
	s_cbranch_execz .LBB0_43
	s_waitcnt lgkmcnt(0)
	buffer_inv sc1
	v_mov_b32_e32 v1, 0x2000
	global_load_dword v1, v1, s[6:7] offset:1024 sc1
	s_add_u32 s20, s6, 0x2400
	s_addc_u32 s21, s7, 0
	s_waitcnt vmcnt(0)
	v_cmp_eq_u32_e32 vcc, v1, v2
	s_and_saveexec_b64 s[14:15], vcc
	s_cbranch_execz .LBB0_42
	s_mov_b32 s11, 1
	s_mov_b64 s[22:23], 0
	v_mov_b32_e32 v1, 0
	s_branch .LBB0_33

.LBB0_42:
	s_or_b64 exec, exec, s[14:15]
	s_waitcnt vmcnt(0)
	s_waitcnt vmcnt(0)

.LBB0_181:
	s_or_b64 exec, exec, s[14:15]
	v_cvt_f32_u32_e32 v5, v3
	s_waitcnt vmcnt(0)
	v_readfirstlane_b32 s11, v4
	v_sub_u32_e32 v4, 0, v3
	v_rcp_iflag_f32_e32 v5, v5
	v_add_u32_e32 v6, s11, v2
	v_mul_f32_e32 v5, 0x4f7ffffe, v5
	v_cvt_u32_f32_e32 v5, v5
	v_mul_lo_u32 v2, v4, v5
	v_mul_hi_u32 v2, v5, v2
	v_add_u32_e32 v2, v5, v2
	v_mul_hi_u32 v2, v6, v2
	v_mul_lo_u32 v4, v2, v3
	v_sub_u32_e32 v4, v6, v4
	v_add_u32_e32 v5, 1, v2
	v_cmp_ge_u32_e32 vcc, v4, v3
	s_nop 1
	v_cndmask_b32_e32 v2, v2, v5, vcc
	v_sub_u32_e32 v5, v4, v3
	v_cndmask_b32_e32 v4, v4, v5, vcc
	v_add_u32_e32 v5, 1, v2
	v_cmp_ge_u32_e32 vcc, v4, v3
	v_add_u32_e32 v4, 1, v6
	s_nop 0
	v_cndmask_b32_e32 v2, v2, v5, vcc
	v_mul_lo_u32 v5, v3, v2
	v_add_u32_e32 v3, v5, v3
	v_cmp_ne_u32_e32 vcc, v4, v3
	s_and_saveexec_b64 s[12:13], vcc
	s_xor_b64 s[12:13], exec, s[12:13]
	s_cbranch_execz .LBB0_195
	s_waitcnt lgkmcnt(0)
	buffer_inv sc1
	v_mov_b32_e32 v1, 0x2000
	global_load_dword v1, v1, s[8:9] offset:1024 sc1
	s_add_u32 s20, s8, 0x2400
	s_addc_u32 s21, s9, 0
	s_waitcnt vmcnt(0)
	v_cmp_eq_u32_e32 vcc, v1, v2
	s_and_saveexec_b64 s[14:15], vcc
	s_cbranch_execz .LBB0_194
	s_mov_b32 s11, 1
	s_mov_b64 s[22:23], 0
	v_mov_b32_e32 v1, 0
	s_branch .LBB0_185

.LBB0_383:
	s_or_b64 exec, exec, s[12:13]
	v_cvt_f32_u32_e32 v5, v3
	s_waitcnt vmcnt(0)
	v_readfirstlane_b32 s8, v4
	v_sub_u32_e32 v4, 0, v3
	v_rcp_iflag_f32_e32 v5, v5
	v_add_u32_e32 v6, s8, v2
	v_mul_f32_e32 v5, 0x4f7ffffe, v5
	v_cvt_u32_f32_e32 v5, v5
	v_mul_lo_u32 v2, v4, v5
	v_mul_hi_u32 v2, v5, v2
	v_add_u32_e32 v2, v5, v2
	v_mul_hi_u32 v2, v6, v2
	v_mul_lo_u32 v4, v2, v3
	v_sub_u32_e32 v4, v6, v4
	v_add_u32_e32 v5, 1, v2
	v_cmp_ge_u32_e32 vcc, v4, v3
	s_nop 1
	v_cndmask_b32_e32 v2, v2, v5, vcc
	v_sub_u32_e32 v5, v4, v3
	v_cndmask_b32_e32 v4, v4, v5, vcc
	v_add_u32_e32 v5, 1, v2
	v_cmp_ge_u32_e32 vcc, v4, v3
	v_add_u32_e32 v4, 1, v6
	s_nop 0
	v_cndmask_b32_e32 v2, v2, v5, vcc
	v_mul_lo_u32 v5, v3, v2
	v_add_u32_e32 v3, v5, v3
	v_cmp_ne_u32_e32 vcc, v4, v3
	s_and_saveexec_b64 s[8:9], vcc
	s_xor_b64 s[8:9], exec, s[8:9]
	s_cbranch_execz .LBB0_397
	s_waitcnt lgkmcnt(0)
	buffer_inv sc1
	v_mov_b32_e32 v1, 0x2000
	global_load_dword v1, v1, s[6:7] offset:1024 sc1
	s_add_u32 s14, s6, 0x2400
	s_addc_u32 s15, s7, 0
	s_waitcnt vmcnt(0)
	v_cmp_eq_u32_e32 vcc, v1, v2
	s_and_saveexec_b64 s[12:13], vcc
	s_cbranch_execz .LBB0_396
	s_mov_b32 s11, 1
	s_mov_b64 s[22:23], 0
	v_mov_b32_e32 v1, 0
	s_branch .LBB0_387

.LBB0_396:
	s_or_b64 exec, exec, s[12:13]
	s_waitcnt vmcnt(0)
	s_waitcnt vmcnt(0)

.LBB0_1042:
	s_or_b64 exec, exec, s[14:15]
	v_cvt_f32_u32_e32 v5, v3
	s_waitcnt vmcnt(0)
	v_readfirstlane_b32 s8, v4
	v_sub_u32_e32 v4, 0, v3
	v_rcp_iflag_f32_e32 v5, v5
	v_add_u32_e32 v6, s8, v2
	v_mul_f32_e32 v5, 0x4f7ffffe, v5
	v_cvt_u32_f32_e32 v5, v5
	v_mul_lo_u32 v2, v4, v5
	v_mul_hi_u32 v2, v5, v2
	v_add_u32_e32 v2, v5, v2
	v_mul_hi_u32 v2, v6, v2
	v_mul_lo_u32 v4, v2, v3
	v_sub_u32_e32 v4, v6, v4
	v_add_u32_e32 v5, 1, v2
	v_cmp_ge_u32_e32 vcc, v4, v3
	s_nop 1
	v_cndmask_b32_e32 v2, v2, v5, vcc
	v_sub_u32_e32 v5, v4, v3
	v_cndmask_b32_e32 v4, v4, v5, vcc
	v_add_u32_e32 v5, 1, v2
	v_cmp_ge_u32_e32 vcc, v4, v3
	v_add_u32_e32 v4, 1, v6
	s_nop 0
	v_cndmask_b32_e32 v2, v2, v5, vcc
	v_mul_lo_u32 v5, v3, v2
	v_add_u32_e32 v3, v5, v3
	v_cmp_ne_u32_e32 vcc, v4, v3
	s_and_saveexec_b64 s[8:9], vcc
	s_xor_b64 s[8:9], exec, s[8:9]
	s_cbranch_execz .LBB0_1056
	s_waitcnt lgkmcnt(0)
	buffer_inv sc1
	v_mov_b32_e32 v1, 0x2000
	global_load_dword v1, v1, s[6:7] offset:1024 sc1
	s_add_u32 s20, s6, 0x2400
	s_addc_u32 s21, s7, 0
	s_waitcnt vmcnt(0)
	v_cmp_eq_u32_e32 vcc, v1, v2
	s_and_saveexec_b64 s[14:15], vcc
	s_cbranch_execz .LBB0_1055
	s_mov_b32 s11, 1
	s_mov_b64 s[22:23], 0
	v_mov_b32_e32 v1, 0
	s_branch .LBB0_1046

.LBB0_2506:
	s_or_b64 exec, exec, s[12:13]
	v_cvt_f32_u32_e32 v5, v3
	s_waitcnt vmcnt(0)
	v_readfirstlane_b32 s8, v4
	v_sub_u32_e32 v4, 0, v3
	v_rcp_iflag_f32_e32 v5, v5
	v_add_u32_e32 v6, s8, v2
	v_mul_f32_e32 v5, 0x4f7ffffe, v5
	v_cvt_u32_f32_e32 v5, v5
	v_mul_lo_u32 v2, v4, v5
	v_mul_hi_u32 v2, v5, v2
	v_add_u32_e32 v2, v5, v2
	v_mul_hi_u32 v2, v6, v2
	v_mul_lo_u32 v4, v2, v3
	v_sub_u32_e32 v4, v6, v4
	v_add_u32_e32 v5, 1, v2
	v_cmp_ge_u32_e32 vcc, v4, v3
	s_nop 1
	v_cndmask_b32_e32 v2, v2, v5, vcc
	v_sub_u32_e32 v5, v4, v3
	v_cndmask_b32_e32 v4, v4, v5, vcc
	v_add_u32_e32 v5, 1, v2
	v_cmp_ge_u32_e32 vcc, v4, v3
	v_add_u32_e32 v4, 1, v6
	s_nop 0
	v_cndmask_b32_e32 v2, v2, v5, vcc
	v_mul_lo_u32 v5, v3, v2
	v_add_u32_e32 v3, v5, v3
	v_cmp_ne_u32_e32 vcc, v4, v3
	s_and_saveexec_b64 s[8:9], vcc
	s_xor_b64 s[8:9], exec, s[8:9]
	s_cbranch_execz .LBB0_2520
	s_waitcnt lgkmcnt(0)
	buffer_inv sc1
	v_mov_b32_e32 v1, 0x2000
	global_load_dword v1, v1, s[6:7] offset:1024 sc1
	s_add_u32 s14, s6, 0x2400
	s_addc_u32 s15, s7, 0
	s_waitcnt vmcnt(0)
	v_cmp_eq_u32_e32 vcc, v1, v2
	s_and_saveexec_b64 s[12:13], vcc
	s_cbranch_execz .LBB0_2519
	s_mov_b32 s11, 1
	s_mov_b64 s[18:19], 0
	v_mov_b32_e32 v1, 0
	s_branch .LBB0_2510
